# static s_setprio 1 for waves 0-3 (the other half) around each hand-written attention loop, on v53
# baseline (speedup 1.0000x reference)
; #define LDS_BARRIER() asm volatile("s_waitcnt lgkmcnt(0)\n\ts_barrier" ::: "memory")
; template <int MODE>
; DI void attn_item(const Params& p, int layer, int bh, int qb, char* lds) {
;     ...
;   f32x16 O[NMAP][2]; float m = 0.f, l[NMAP];
; #pragma unroll
;   for (int mp = 0; mp < NMAP; ++mp) {
; #pragma unroll
;     for (int r = 0; r < 16; ++r) { O[mp][0][r] = 0.f; O[mp][1][r] = 0.f; }
;     l[mp] = 0.f;
;   }
;   if (MODE == 2) { m = p.sink[layer * 6 + hd] * LOG2E; l[0] = (hh == 0) ? 1.f : 0.f; }
;   int kt0 = 0, kt1 = S / 64;
;   if (MODE == 2) { kt0 = (q0 - 128) / 64; if (kt0 < 0) kt0 = 0; kt1 = (q0 + 384) / 64; if (kt1 > S / 64) kt1 = S / 64; }
;   const int nt = kt1 - kt0;
;   constexpr int KSTRG = MODE == 0 ? 96 : 64, VSTRG = 64;
;   u32x4 rkA[KCH], rvA[1], rkB[KCH], rvB[1];
;   const __amdgpu_buffer_rsrc_t krsrc = __builtin_amdgcn_make_buffer_rsrc((void*)Kg, 0, S * KSTRG * 2, 0x00027000);
;   const __amdgpu_buffer_rsrc_t vrsrc = __builtin_amdgcn_make_buffer_rsrc((void*)Vg, 0, S * VSTRG * 2, 0x00027000);
;     ...
;   __syncthreads();
;   gload(kt0, rkA, rvA); lstore(0, rkA, rvA);
;   if (nt > 1) gload(kt0 + 1, rkB, rvB);
;   LDS_BARRIER();
;   for (int t = 0; t < nt; t += 2) {
.LBB0_334:
	s_or_b64 exec, exec, s[8:9]
	s_and_b32 s9, 0xffff, s21
	s_mul_i32 s6, s9, 0x2b80000
	s_add_u32 s6, s34, s6
	s_addc_u32 s7, s35, 0
	s_lshl_b32 s8, s20, 7
	s_add_u32 s6, s6, s8
	s_addc_u32 s7, s7, 0
	s_add_u32 s6, s6, 0x60589c0
	v_ashrrev_i32_e32 v1, 1, v0
	s_addc_u32 s7, s7, 0
	v_and_b32_e32 v1, 0xffffffe0, v1
	s_cmp_gt_u32 s20, 2
	v_and_b32_e32 v222, 31, v0
	v_add_u32_e32 v186, s23, v1
	s_cselect_b32 s8, 0x100000, 0
	s_lshl_b32 s10, s9, 21
	s_or_b32 s8, s10, s8
	v_readlane_b32 s10, v254, 37
	v_or_b32_e32 v3, v186, v222
	v_mov_b64_e32 v[6:7], s[6:7]
	v_readlane_b32 s11, v254, 38
	s_add_u32 s24, s10, s8
	v_mad_i64_i32 v[6:7], s[6:7], v3, s64, v[6:7]
	s_addc_u32 s10, s11, 0
	v_readlane_b32 s12, v254, 35
	v_readlane_b32 s6, v255, 40
	v_bfe_u32 v2, v0, 5, 1
	v_readlane_b32 s13, v254, 36
	s_add_u32 s12, s12, s8
	s_mul_i32 s6, s6, 6
	s_addc_u32 s11, s13, 0
	v_lshlrev_b32_e32 v188, 4, v2
	v_mov_b32_e32 v189, v5
	v_readlane_b32 s7, v255, 41
	s_add_i32 s52, s6, s20
	v_lshl_add_u64 v[6:7], v[6:7], 0, v[188:189]
	s_lshl_b64 s[6:7], s[52:53], 2
	global_load_dwordx4 v[112:115], v[6:7], off
	global_load_dwordx4 v[116:119], v[6:7], off offset:32
	global_load_dwordx4 v[120:123], v[6:7], off offset:64
	global_load_dwordx4 v[124:127], v[6:7], off offset:96
	s_add_u32 s6, s80, s6
	s_addc_u32 s7, s81, s7
	global_load_dword v3, v5, s[6:7]
	s_add_i32 s6, s23, 0xffffff80
	s_ashr_i32 s6, s6, 6
	v_mov_b32_e32 v6, v5
	v_mov_b32_e32 v7, v5
	s_max_i32 s8, s6, 0
	v_mov_b32_e32 v4, v5
	v_mov_b64_e32 v[130:131], v[6:7]
	s_and_b32 s25, s10, 0xffff
	s_lshl_b32 s10, s8, 13
	v_lshlrev_b32_e32 v187, 4, v0
	v_mov_b64_e32 v[128:129], v[4:5]
	s_waitcnt lgkmcnt(0)
	s_barrier
	s_and_b32 s13, s11, 0xffff
	s_mov_b32 s26, s14
	s_mov_b32 s27, s15
	s_lshl_b32 s52, s9, 13
	s_lshl_b32 s63, s20, 6
	s_mov_b32 s93, s10
	s_mov_b32 s28, s8
	s_add_i32 s29, s23, 0x180
	s_lshr_b32 s29, s29, 6
	s_min_u32 s29, s29, 0x80
	s_sub_u32 s62, s29, s8
	v_readfirstlane_b32 s49, v186
	s_nop 0
	s_add_i32 s10, s49, 0xffffff80
	s_ashr_i32 s10, s10, 6
	s_max_i32 s10, s10, s8
	s_add_i32 s11, s49, 0x9f
	s_lshr_b32 s11, s11, 6
	s_add_u32 s11, s11, 1
	s_min_u32 s11, s11, s29
	v_bfe_u32 v15, v184, 5, 1
	v_lshlrev_b32_e32 v189, 2, v15
	v_mov_b32_e32 v200, 144
	v_mul_u32_u24_e32 v206, v222, v200
	v_lshl_add_u32 v206, v15, 4, v206
	v_bfe_u32 v200, v184, 2, 2
	v_lshl_add_u32 v200, v15, 2, v200
	v_mov_b32_e32 v201, 192
	v_mul_u32_u24_e32 v207, v200, v201
	v_bfe_u32 v200, v184, 4, 1
	v_lshl_add_u32 v207, v200, 5, v207
	v_and_b32_e32 v200, 3, v184
	v_lshl_add_u32 v207, v200, 3, v207
	v_lshrrev_b32_e32 v14, 3, v184
	v_and_b32_e32 v200, 7, v184
	v_mov_b32_e32 v201, 144
	v_mul_u32_u24_e32 v208, v14, v201
	v_lshl_add_u32 v208, v200, 4, v208
	v_mov_b32_e32 v201, 192
	v_mul_u32_u24_e32 v209, v14, v201
	v_lshl_add_u32 v209, v200, 4, v209
	v_cmp_eq_u32_e64 s[6:7], 0, v15
	v_sub_u32_e32 v14, v189, v222
	v_sub_u32_e32 v14, v14, v186
	v_add_u32_e32 v14, 0xe0, v14
	v_lshlrev_b32_e32 v210, 2, v14
	buffer_load_dwordx4 v[128:131], v187, s[24:27], s93 offen
	buffer_load_dwordx4 v[132:135], v187, s[12:15], s93 offen
	s_add_u32 s93, s93, 0x2000
	buffer_load_dwordx4 v[248:251], v187, s[24:27], s93 offen
	buffer_load_dwordx4 v[224:227], v187, s[12:15], s93 offen
	s_add_u32 s93, s93, 0x2000
	s_waitcnt vmcnt(2)
	ds_write_b128 v208, v[128:131] offset:2048
	ds_write_b128 v209, v[132:135] offset:11264
	v_mul_f32_e32 v204, 0x3fb8aa3b, v3
	v_cndmask_b32_e64 v231, 0, 1.0, s[6:7]
	v_sub_f32_e32 v200, 0, v204
	v_bfe_u32 v15, v200, 16, 1
	v_add3_u32 v14, v200, v15, s45
	v_lshrrev_b32_e32 v15, 16, v14
	v_and_b32_e32 v14, 0xffff0000, v14
	v_sub_f32_e32 v14, v200, v14
	v_bfe_u32 v200, v14, 16, 1
	v_add3_u32 v14, v14, v200, s45
	v_and_or_b32 v14, v14, s92, v15
	v_cndmask_b32_e64 v140, 0, v14, s[6:7]
	v_mov_b32_e32 v14, 0x3f803f80
	v_cndmask_b32_e64 v136, 0, v14, s[6:7]
	v_mov_b32_e32 v137, 0
	v_mov_b32_e32 v141, 0
	v_mov_b32_e32 v138, 0
	v_mov_b32_e32 v142, 0
	v_mov_b32_e32 v139, 0
	v_mov_b32_e32 v143, 0
	s_nop 1
	v_mfma_f32_32x32x16_bf16 v[48:63], v[136:139], v[140:143], 0
	v_mov_b32_e32 v16, 0
	v_mov_b32_e32 v32, 0
	v_mov_b32_e32 v17, 0
	v_mov_b32_e32 v33, 0
	v_mov_b32_e32 v18, 0
	v_mov_b32_e32 v34, 0
	v_mov_b32_e32 v19, 0
	v_mov_b32_e32 v35, 0
	v_mov_b32_e32 v20, 0
	v_mov_b32_e32 v36, 0
	v_mov_b32_e32 v21, 0
	v_mov_b32_e32 v37, 0
	v_mov_b32_e32 v22, 0
	v_mov_b32_e32 v38, 0
	v_mov_b32_e32 v23, 0
	v_mov_b32_e32 v39, 0
	v_mov_b32_e32 v24, 0
	v_mov_b32_e32 v40, 0
	v_mov_b32_e32 v25, 0
	v_mov_b32_e32 v41, 0
	v_mov_b32_e32 v26, 0
	v_mov_b32_e32 v42, 0
	v_mov_b32_e32 v27, 0
	v_mov_b32_e32 v43, 0
	v_mov_b32_e32 v28, 0
	v_mov_b32_e32 v44, 0
	v_mov_b32_e32 v29, 0
	v_mov_b32_e32 v45, 0
	v_mov_b32_e32 v30, 0
	v_mov_b32_e32 v46, 0
	v_mov_b32_e32 v31, 0
	v_mov_b32_e32 v47, 0
	v_mov_b32_e32 v205, 0
	s_waitcnt lgkmcnt(0)
	s_barrier
	v_readfirstlane_b32 s29, v184
	s_nop 3
	s_cmpk_lt_u32 s29, 0x100
	s_cbranch_scc0 .Lsw_prio
	s_setprio 1

; template <int MODE>
; DI void attn_item(const Params& p, int layer, int bh, int qb, char* lds) {
;     ...
;   bf16x8 qf[NMAP][QS];
;   {
;     const u16* qrow = Qg + (size_t)(q0w + l32) * qstr + hh * 8;
; #pragma unroll
;     for (int mp = 0; mp < NMAP; ++mp)
; #pragma unroll
;       for (int st = 0; st < QS; ++st) qf[mp][st] = *(const bf16x8*)(qrow + (mp * QS + st) * 16);
;   }
;   f32x16 O[NMAP][2]; float m = 0.f, l[NMAP];
; #pragma unroll
;   for (int mp = 0; mp < NMAP; ++mp) {
; #pragma unroll
;     for (int r = 0; r < 16; ++r) { O[mp][0][r] = 0.f; O[mp][1][r] = 0.f; }
;     l[mp] = 0.f;
;   }
;   if (MODE == 2) { m = p.sink[layer * 6 + hd] * LOG2E; l[0] = (hh == 0) ? 1.f : 0.f; }
;   int kt0 = 0, kt1 = S / 64;
;   if (MODE == 2) { kt0 = (q0 - 128) / 64; if (kt0 < 0) kt0 = 0; kt1 = (q0 + 384) / 64; if (kt1 > S / 64) kt1 = S / 64; }
;   const int nt = kt1 - kt0;
;   constexpr int KSTRG = MODE == 0 ? 96 : 64, VSTRG = 64;
;   u32x4 rkA[KCH], rvA[1], rkB[KCH], rvB[1];
;   const __amdgpu_buffer_rsrc_t krsrc = __builtin_amdgcn_make_buffer_rsrc((void*)Kg, 0, S * KSTRG * 2, 0x00027000);
;   const __amdgpu_buffer_rsrc_t vrsrc = __builtin_amdgcn_make_buffer_rsrc((void*)Vg, 0, S * VSTRG * 2, 0x00027000);
;   auto gload = [&](int kt, u32x4 (&rk)[KCH], u32x4 (&rv)[1]) {
;     const int ksoff = kt * (64 * KSTRG * 2), vsoff = kt * (64 * VSTRG * 2);
; #pragma unroll
;     for (int i = 0; i < KCH; ++i) if (tid + NTHR * i < KCHUNKS) rk[i] = __builtin_amdgcn_raw_buffer_load_b128(krsrc, tid * 16 + NTHR * 16 * i, ksoff, 0);
;     rv[0] = __builtin_amdgcn_raw_buffer_load_b128(vrsrc, tid * 16, vsoff, 0);
;   };
;   auto lstore = [&](int st, const u32x4 (&rk)[KCH], const u32x4 (&rv)[1]) {
;     char* Ks = stage0 + st * STAGE;
; #pragma unroll
;     for (int i = 0; i < KCH; ++i) { int c = tid + NTHR * i, row = c / KCPR, ch = c % KCPR; if (c < KCHUNKS) *(u32x4*)(Ks + row * KSTR + ch * 16) = rk[i]; }
;     { int row = tid >> 3, ch = tid & 7; *(u32x4*)(Ks + KBYTES + row * VSTR + ch * 16) = rv[0]; }
;   };
;   const unsigned vlane = (unsigned)((4 * hh + ((lane & 15) >> 2)) * VSTR + 32 * ((lane >> 4) & 1) + 8 * (lane & 3));
;   bf16x8 kaug, qaug;
;   { u32x4 tk = {hh == 0 ? 0x3F803F80u : 0u, 0u, 0u, 0u}; kaug = __builtin_bit_cast(bf16x8, tk); qaug = __builtin_bit_cast(bf16x8, (u32x4){0u, 0u, 0u, 0u}); }
;     ...
;   __syncthreads();
;   gload(kt0, rkA, rvA); lstore(0, rkA, rvA);
.LBB0_403:
	s_ashr_i32 s5, s60, 5
	s_and_b32 s4, s60, 7
	s_and_b32 s5, s5, -8
	v_mov_b32_e32 v14, v184
	s_or_b32 s4, s5, s4
	s_lshl_b32 s5, s60, 5
	s_waitcnt vmcnt(0)
	v_ashrrev_i32_e32 v0, 1, v14
	s_and_b32 s5, s5, 0x1f00
	v_and_b32_e32 v0, 0xffffffe0, v0
	v_add_u32_e32 v186, s5, v0
	s_mul_hi_i32 s5, s4, 0x2aaaaaab
	s_lshr_b32 s6, s5, 31
	s_add_i32 s10, s5, s6
	s_mul_i32 s5, s10, 6
	s_sub_i32 s52, s4, s5
	s_mul_i32 s6, s10, 0x900000
	v_readlane_b32 s8, v254, 45
	s_mul_hi_i32 s5, s10, 0x900000
	v_readlane_b32 s9, v254, 46
	s_add_u32 s8, s8, s6
	s_mul_i32 s6, s52, 0x60
	s_addc_u32 s5, s9, s5
	s_ashr_i32 s7, s6, 31
	s_lshl_b64 s[6:7], s[6:7], 1
	s_add_u32 s6, s8, s6
	v_and_b32_e32 v204, 31, v14
	s_addc_u32 s7, s5, s7
	v_bfe_u32 v15, v14, 5, 1
	v_or_b32_e32 v2, v186, v204
	v_mov_b64_e32 v[0:1], s[6:7]
	s_movk_i32 s5, 0x480
	v_mad_i64_i32 v[0:1], s[6:7], v2, s5, v[0:1]
	v_lshlrev_b32_e32 v16, 4, v15
	v_mov_b32_e32 v17, v5
	v_lshl_add_u64 v[0:1], v[0:1], 0, v[16:17]
	global_load_dwordx4 v[104:107], v[0:1], off
	global_load_dwordx4 v[108:111], v[0:1], off offset:32
	global_load_dwordx4 v[112:115], v[0:1], off offset:64
	global_load_dwordx4 v[116:119], v[0:1], off offset:96
	global_load_dwordx4 v[120:123], v[0:1], off offset:128
	global_load_dwordx4 v[124:127], v[0:1], off offset:160
	s_ashr_i32 s5, s4, 31
	s_mul_hi_i32 s6, s4, 0x180000
	s_mul_i32 s7, s4, 0x180000
	s_lshl_b64 s[4:5], s[4:5], 20
	s_add_u32 s12, s68, s4
	s_addc_u32 s11, s69, s5
	s_add_u32 s20, s66, s7
	s_addc_u32 s4, s67, s6
	s_and_b32 s21, s4, 0xffff
	s_movk_i32 s4, 0x300
	v_cmp_gt_i32_e64 s[4:5], s4, v14
	v_lshlrev_b32_e32 v187, 4, v14
	v_mov_b32_e32 v100, 0
	v_mov_b32_e32 v96, 0
	v_mov_b32_e32 v97, 0
	v_mov_b32_e32 v98, 0
	v_mov_b32_e32 v99, 0
	s_barrier
	s_and_b32 s13, s11, 0xffff
	s_ashr_i32 s11, s10, 31
	s_mov_b32 s23, s15
	v_bfe_u32 v206, v184, 5, 1
	v_lshlrev_b32_e32 v206, 2, v206
	v_and_b32_e32 v196, 31, v184
	v_bfe_u32 v197, v184, 5, 1
	v_mov_b32_e32 v199, 208
	v_mul_u32_u24_e32 v200, v196, v199
	v_lshl_add_u32 v200, v197, 4, v200
	v_bfe_u32 v199, v184, 2, 2
	v_lshl_add_u32 v199, v197, 2, v199
	v_mov_b32_e32 v208, 192
	v_mul_u32_u24_e32 v201, v199, v208
	v_bfe_u32 v199, v184, 4, 1
	v_lshl_add_u32 v201, v199, 5, v201
	v_and_b32_e32 v199, 3, v184
	v_lshl_add_u32 v201, v199, 3, v201
	v_mov_b32_e32 v208, 0xaaab
	v_mul_u32_u24_e32 v196, v184, v208
	v_lshrrev_b32_e32 v196, 19, v196
	v_mul_u32_u24_e32 v197, 12, v196
	v_sub_u32_e32 v197, v184, v197
	v_mov_b32_e32 v199, 208
	v_mul_u32_u24_e32 v202, v196, v199
	v_lshl_add_u32 v202, v197, 4, v202
	v_lshrrev_b32_e32 v196, 1, v184
	v_add_u32_e32 v196, 0x200, v196
	v_mul_u32_u24_e32 v197, v196, v208
	v_lshrrev_b32_e32 v197, 19, v197
	v_mul_u32_u24_e32 v209, 12, v197
	v_sub_u32_e32 v196, v196, v209
	v_mul_u32_u24_e32 v203, v197, v199
	v_lshl_add_u32 v203, v196, 4, v203
	v_and_b32_e32 v196, 1, v184
	v_lshl_add_u32 v203, v196, 3, v203
	v_lshrrev_b32_e32 v196, 3, v184
	v_mov_b32_e32 v199, 192
	v_mul_u32_u24_e32 v207, v196, v199
	v_and_b32_e32 v196, 7, v184
	v_lshl_add_u32 v207, v196, 4, v207
	v_lshlrev_b32_e32 v187, 4, v184
	v_lshlrev_b32_e32 v205, 3, v184
	v_add_u32_e32 v205, 0x2000, v205
	v_bfe_u32 v197, v184, 5, 1
	v_cmp_eq_u32_e64 s[8:9], 0, v197
	v_mov_b32_e32 v196, 0x3f803f80
	s_nop 0
	v_cndmask_b32_e64 v240, 0, v196, s[8:9]
	v_mov_b32_e32 v241, 0
	v_mov_b32_e32 v245, 0
	v_mov_b32_e32 v242, 0
	v_mov_b32_e32 v246, 0
	v_mov_b32_e32 v243, 0
	v_mov_b32_e32 v247, 0
	buffer_load_dwordx4 v[64:67], v187, s[20:23], 0 offen
	buffer_load_dwordx2 v[68:69], v205, s[20:23], 0 offen
	buffer_load_dwordx4 v[72:75], v187, s[12:15], 0 offen
	s_movk_i32 s62, 0x3000
	buffer_load_dwordx4 v[76:79], v187, s[20:23], s62 offen
	buffer_load_dwordx2 v[80:81], v205, s[20:23], s62 offen
	s_waitcnt vmcnt(0)
	ds_write_b128 v202, v[64:67] offset:2048
	ds_write_b64 v203, v[68:69] offset:2048
	ds_write_b128 v207, v[72:75] offset:15360
	ds_write_b128 v202, v[76:79] offset:27648
	ds_write_b64 v203, v[80:81] offset:27648
	s_movk_i32 s62, 0x6000
	s_movk_i32 s29, 0x2000
	buffer_load_dwordx4 v[96:99], v187, s[20:23], s62 offen
	buffer_load_dwordx2 v[100:101], v205, s[20:23], s62 offen
	buffer_load_dwordx4 v[188:191], v187, s[12:15], s29 offen
	s_mov_b32 s62, 0x9000
	s_movk_i32 s29, 0x4000
	buffer_load_dwordx4 v[230:233], v187, s[20:23], s62 offen
	buffer_load_dwordx2 v[234:235], v205, s[20:23], s62 offen
	buffer_load_dwordx4 v[236:239], v187, s[12:15], s29 offen
	s_mov_b32 s62, 0xc000
	s_movk_i32 s29, 0x6000
	s_waitcnt lgkmcnt(0)
	s_barrier
; template <int MODE>
; DI void attn_item(const Params& p, int layer, int bh, int qb, char* lds) {
;     ...
;         f32x16 s[2];
;         const f32x16 zero16 = {0.f, 0.f, 0.f, 0.f, 0.f, 0.f, 0.f, 0.f, 0.f, 0.f, 0.f, 0.f, 0.f, 0.f, 0.f, 0.f};
;         __builtin_amdgcn_s_setprio(1);
;         f32x16 c0tile;
;         c0tile = c0p;
; #pragma unroll
;         for (int sub = 0; sub < 2; ++sub) {
; #pragma unroll
;           for (int st = 0; st < QS; ++st) {
;             bf16x8 kf = *(const bf16x8*)(Ks + (32 * sub + l32) * KSTR + ((mp * QS + st) * 16 + hh * 8) * 2);
;             if (st == 0) s[sub] = MFMA(kf, qf[mp][st], c0tile); else s[sub] = MFMA(kf, qf[mp][st], s[sub]);
;           }
;         }
;         __builtin_amdgcn_iglp_opt(1);
;         __builtin_amdgcn_s_setprio(0);
;         if (NMAP == 1) {
;           lds_s16x4* vb = (lds_s16x4*)(Ks + KBYTES + vlane);
; #pragma unroll
;           for (int i = 0; i < 16; ++i) {
;             const int sub_ = i >> 3, ks_ = (i >> 2) & 1, dt_ = (i >> 1) & 1, g_ = i & 1;
;             vpre[i] = __builtin_amdgcn_ds_read_tr16_b64_v4i16(vb + ((32 * sub_ + 16 * ks_ + 8 * g_) * VSTR + 64 * dt_) / 8);
;           }
;           __builtin_amdgcn_sched_barrier(0);
;         }
;         if (MODE != 0 && !far) {
; #pragma unroll
;           for (int sub = 0; sub < 2; ++sub)
; #pragma unroll
;             for (int r = 0; r < 16; ++r) s[sub][r] += brow[32 * sub + (r & 3) + 8 * (r >> 2)];
;         }
;         const bool first = (MODE != 2) && (t == 0) && (mp == 0);
;         auto rebase = [&]() {
;           float mx = fmaxf(fmaxf(s[0][0], s[0][1]), s[0][2]);
; #pragma unroll
;           for (int r = 3; r < 15; r += 2) mx = fmaxf(fmaxf(mx, s[0][r]), s[0][r + 1]);
;           mx = fmaxf(mx, s[0][15]);
; #pragma unroll
;           for (int r = 0; r < 16; r += 2) mx = fmaxf(fmaxf(mx, s[1][r]), s[1][r + 1]);
;           const float rm = xchg_max(mx);
;           float delta = first ? rm : fmaxf(rm, 0.f);
;           if (delta < -1e29f) delta = 0.f;
;           m += delta;
;           const float alpha = __builtin_amdgcn_exp2f(-delta);
; #pragma unroll
;           for (int mq = 0; mq < NMAP; ++mq) {
;             l[mq] *= alpha;
; #pragma unroll
;             for (int r = 0; r < 16; ++r) { O[mq][0][r] *= alpha; O[mq][1][r] *= alpha; }
;           }
; #pragma unroll
	ds_read_b128 v[176:179], v200 offset:2048
	ds_read_b128 v[180:183], v200 offset:2080
	ds_read_b128 v[222:225], v200 offset:2112
	s_waitcnt lgkmcnt(2)
	v_mfma_f32_32x32x16_bf16 v[64:79], v[176:179], v[104:107], 0
	ds_read_b128 v[226:229], v200 offset:2144
	s_waitcnt lgkmcnt(2)
	v_mfma_f32_32x32x16_bf16 v[64:79], v[180:183], v[108:111], v[64:79]
	ds_read_b128 v[176:179], v200 offset:2176
	s_waitcnt lgkmcnt(2)
	v_mfma_f32_32x32x16_bf16 v[64:79], v[222:225], v[112:115], v[64:79]
	ds_read_b128 v[180:183], v200 offset:2208
	s_waitcnt lgkmcnt(2)
	v_mfma_f32_32x32x16_bf16 v[64:79], v[226:229], v[116:119], v[64:79]
	ds_read_b128 v[222:225], v200 offset:8704
	s_waitcnt lgkmcnt(2)
	v_mfma_f32_32x32x16_bf16 v[64:79], v[176:179], v[120:123], v[64:79]
	ds_read_b128 v[226:229], v200 offset:8736
	s_waitcnt lgkmcnt(2)
	v_mfma_f32_32x32x16_bf16 v[64:79], v[180:183], v[124:127], v[64:79]
	ds_read_b128 v[176:179], v200 offset:8768
	s_waitcnt lgkmcnt(2)
	v_mfma_f32_32x32x16_bf16 v[80:95], v[222:225], v[104:107], 0
	ds_read_b128 v[180:183], v200 offset:8800
	s_waitcnt lgkmcnt(2)
	v_mfma_f32_32x32x16_bf16 v[80:95], v[226:229], v[108:111], v[80:95]
	ds_read_b128 v[222:225], v200 offset:8832
	s_waitcnt lgkmcnt(2)
	v_mfma_f32_32x32x16_bf16 v[80:95], v[176:179], v[112:115], v[80:95]
	ds_read_b128 v[226:229], v200 offset:8864
	s_waitcnt lgkmcnt(2)
	v_mfma_f32_32x32x16_bf16 v[80:95], v[180:183], v[116:119], v[80:95]
	s_waitcnt lgkmcnt(1)
	v_mfma_f32_32x32x16_bf16 v[80:95], v[222:225], v[120:123], v[80:95]
	s_waitcnt lgkmcnt(0)
	v_mfma_f32_32x32x16_bf16 v[80:95], v[226:229], v[124:127], v[80:95]
	v_mov_b32_e32 v16, 0
	v_mov_b32_e32 v32, 0
	v_mov_b32_e32 v17, 0
	v_mov_b32_e32 v33, 0
	v_mov_b32_e32 v18, 0
	v_mov_b32_e32 v34, 0
	v_mov_b32_e32 v19, 0
	v_mov_b32_e32 v35, 0
	v_mov_b32_e32 v20, 0
	v_mov_b32_e32 v36, 0
	v_mov_b32_e32 v21, 0
	v_mov_b32_e32 v37, 0
	v_mov_b32_e32 v22, 0
	v_mov_b32_e32 v38, 0
	v_mov_b32_e32 v23, 0
	v_mov_b32_e32 v39, 0
	v_mov_b32_e32 v24, 0
	v_mov_b32_e32 v40, 0
	v_mov_b32_e32 v25, 0
	v_mov_b32_e32 v41, 0
	v_mov_b32_e32 v26, 0
	v_mov_b32_e32 v42, 0
	v_mov_b32_e32 v27, 0
	v_mov_b32_e32 v43, 0
	v_mov_b32_e32 v28, 0
	v_mov_b32_e32 v44, 0
	v_mov_b32_e32 v29, 0
	v_mov_b32_e32 v45, 0
	v_mov_b32_e32 v30, 0
	v_mov_b32_e32 v46, 0
	v_mov_b32_e32 v31, 0
	v_mov_b32_e32 v47, 0
	v_mov_b32_e32 v192, 0
	v_mov_b32_e32 v193, 0
	s_waitcnt lgkmcnt(0)
	s_barrier
	v_max_f32_e32 v196, v64, v65
	v_max3_f32 v196, v196, v66, v67
	v_max3_f32 v196, v196, v68, v69
	v_max3_f32 v196, v196, v70, v71
	v_max3_f32 v196, v196, v72, v73
	v_max3_f32 v196, v196, v74, v75
	v_max3_f32 v196, v196, v76, v77
	v_max3_f32 v196, v196, v78, v79
	v_max3_f32 v196, v196, v80, v81
	v_max3_f32 v196, v196, v82, v83
	v_max3_f32 v196, v196, v84, v85
	v_max3_f32 v196, v196, v86, v87
	v_max3_f32 v196, v196, v88, v89
	v_max3_f32 v196, v196, v90, v91
	v_max3_f32 v196, v196, v92, v93
	v_max3_f32 v196, v196, v94, v95
	v_mov_b32_e32 v197, v196
	s_nop 1
	v_permlane32_swap_b32_e32 v196, v197
	v_max_f32_e32 v196, v196, v197
	s_mov_b32 s24, 0xefa18f08
	v_cmp_ngt_f32_e32 vcc, s24, v196
	s_nop 1
	v_cndmask_b32_e32 v198, 0, v196, vcc
	v_sub_f32_e32 v64, v64, v198
	v_sub_f32_e32 v65, v65, v198
	v_sub_f32_e32 v66, v66, v198
	v_sub_f32_e32 v67, v67, v198
	v_sub_f32_e32 v68, v68, v198
	v_sub_f32_e32 v69, v69, v198
	v_sub_f32_e32 v70, v70, v198
	v_sub_f32_e32 v71, v71, v198
	v_sub_f32_e32 v72, v72, v198
	v_sub_f32_e32 v73, v73, v198
	v_sub_f32_e32 v74, v74, v198
	v_sub_f32_e32 v75, v75, v198
	v_sub_f32_e32 v76, v76, v198
	v_sub_f32_e32 v77, v77, v198
	v_sub_f32_e32 v78, v78, v198
	v_sub_f32_e32 v79, v79, v198
	v_sub_f32_e32 v80, v80, v198
	v_sub_f32_e32 v81, v81, v198
	v_sub_f32_e32 v82, v82, v198
	v_sub_f32_e32 v83, v83, v198
	v_sub_f32_e32 v84, v84, v198
	v_sub_f32_e32 v85, v85, v198
	v_sub_f32_e32 v86, v86, v198
	v_sub_f32_e32 v87, v87, v198
	v_sub_f32_e32 v88, v88, v198
	v_sub_f32_e32 v89, v89, v198
	v_sub_f32_e32 v90, v90, v198
	v_sub_f32_e32 v91, v91, v198
	v_sub_f32_e32 v92, v92, v198
	v_sub_f32_e32 v93, v93, v198
	v_sub_f32_e32 v94, v94, v198
	v_sub_f32_e32 v95, v95, v198
	v_sub_f32_e32 v196, 0, v198
	v_bfe_u32 v197, v196, 16, 1
	v_add3_u32 v196, v196, v197, s45
	v_lshrrev_b32_e32 v197, 16, v196
	v_and_b32_e32 v196, 0xffff0000, v196
	v_sub_f32_e64 v196, -v198, v196
	v_bfe_u32 v199, v196, 16, 1
	v_add3_u32 v196, v196, v199, s45
	v_and_or_b32 v196, v196, s92, v197
	v_cndmask_b32_e64 v244, 0, v196, s[8:9]
	s_nop 1
	v_mfma_f32_32x32x16_bf16 v[48:63], v[240:243], v[244:247], 0
	s_mov_b32 s28, 0
	v_readfirstlane_b32 s24, v184
	s_nop 3
	s_cmpk_lt_u32 s24, 0x100
	s_cbranch_scc0 .Lmla_prio
	s_setprio 1

; #define MFMA(a, b, c) __builtin_amdgcn_mfma_f32_32x32x16_bf16((a), (b), (c), 0, 0, 0)
; template <int MODE>
; DI void attn_item(const Params& p, int layer, int bh, int qb, char* lds) {
;     ...
;             bf16x8 kf = *(const bf16x8*)(Ks + (32 * sub + l32) * KSTR + ((mp * QS + st) * 16 + hh * 8) * 2);
;             if (st == 0) s[sub] = MFMA(kf, qf[mp][st], c0tile); else s[sub] = MFMA(kf, qf[mp][st], s[sub]);
;           }
;         }
;         __builtin_amdgcn_iglp_opt(1);
;         __builtin_amdgcn_s_setprio(0);
;         if (NMAP == 1) {
;           lds_s16x4* vb = (lds_s16x4*)(Ks + KBYTES + vlane);
; #pragma unroll
;           for (int i = 0; i < 16; ++i) {
;             const int sub_ = i >> 3, ks_ = (i >> 2) & 1, dt_ = (i >> 1) & 1, g_ = i & 1;
;             vpre[i] = __builtin_amdgcn_ds_read_tr16_b64_v4i16(vb + ((32 * sub_ + 16 * ks_ + 8 * g_) * VSTR + 64 * dt_) / 8);
;           }
;           __builtin_amdgcn_sched_barrier(0);
;         }
.Ldf_p_c0d:
	s_nop 11
	s_mov_b32 s62, 0
	ds_read_b64_tr_b16 v[222:223], v205 offset:54272
	ds_read_b64_tr_b16 v[224:225], v205 offset:55808
	ds_read_b64_tr_b16 v[226:227], v205 offset:54336
	ds_read_b64_tr_b16 v[228:229], v205 offset:55872
	ds_read_b128 v[230:233], v204 offset:2112
	v_readfirstlane_b32 s4, v184
	s_nop 3
	s_cmpk_lt_u32 s4, 0x100
	s_cbranch_scc0 .Ldf_prio
	s_setprio 1
